# rout: state-row loads prefetched two half-bodies ahead into a second register set (counted vmcnt)
# baseline (speedup 1.0000x reference)
; #define LAS __attribute__((address_space(3)))
; #define RO_WRITE(rv, rs, buf) do { _Pragma("unroll") for (int i = 0; i < 2; ++i) { const int q = tid + 512 * i; *(LAS v4u*)(lds + (buf) + (q >> 4) * VROW + (q & 15) * 16) = rv[i]; } \
;             if (cross) { _Pragma("unroll") for (int i = 0; i < 4; ++i) { const int q = tid + 512 * i; *(LAS v4u*)(lds + (buf) + VTB + (q >> 5) * SROW + (q & 31) * 16) = rs[i]; } } } while (0)
; __device__ __forceinline__ void ret_out_phase(LAS unsigned char* lds, const bf16* PROJ, const bf16* KVT, const bf16* ST, bf16* Y, float* RN, int G, int bid) {
;     ...
;         v4u rvA[2], rsA[4];
;     ...
;         RO_LOAD(rvA, rsA, 0); RO_WRITE(rvA, rsA, BUF0);
;     ...
;         const float lgam = log2f(1.0f - exp2f(-5.0f - (float)h)); const float rsc = exp2f(lgam * (float)(n0 + li + 1));
;         float q2 = 0.f;
;         LAS unsigned char* stg = lds + 120832 + w * 2304;
;         const bf16* grow_ = PROJ + (size_t)(t0 + n0 + (lane >> 3)) * 6144 + 2048 + h * 512 + (lane & 7) * 8;
.LBB0_128:
	v_cvt_f32_i32_e32 v3, s2
	s_mov_b32 s12, 0xc2fc0000
	s_and_b32 s3, s16, 63
	s_lshl_b32 s11, s3, 7
	v_sub_f32_e32 v3, 0xc0a00000, v3
	v_cmp_gt_f32_e32 vcc, s12, v3
	s_and_b64 s[4:5], vcc, exec
	s_cselect_b32 s3, 0xffffffc0, 0
	v_cndmask_b32_e32 v40, 0, v221, vcc
	v_add_f32_e32 v3, v3, v40
	v_exp_f32_e32 v3, v3
	v_mov_b32_e32 v40, 0x42000000
	s_mulk_i32 s1, 0x900
	v_and_b32_e32 v46, 0x70, v101
	v_ldexp_f32 v3, v3, s3
	v_sub_f32_e32 v3, 1.0, v3
	s_mov_b32 s3, 0x800000
	v_cmp_gt_f32_e32 vcc, s3, v3
	s_and_b64 s[4:5], vcc, exec
	s_cselect_b32 s3, 32, 0
	v_ldexp_f32 v3, v3, s3
	v_log_f32_e32 v41, v3
	v_add3_u32 v3, v98, s10, 1
	v_cvt_f32_i32_e32 v42, v3
	v_cndmask_b32_e32 v40, 0, v40, vcc
	v_sub_f32_e32 v40, v41, v40
	s_add_i32 s1, s1, 0
	v_mul_f32_e32 v41, v40, v42
	v_cmp_gt_f32_e32 vcc, s12, v41
	s_add_i32 s4, s1, 0x1d800
	v_and_b32_e32 v158, 63, v111
	v_cndmask_b32_e32 v41, 0, v221, vcc
	v_fmac_f32_e32 v41, v40, v42
	v_exp_f32_e32 v40, v41
	v_not_b32_e32 v41, 63
	v_cndmask_b32_e32 v41, 0, v41, vcc
	s_movk_i32 s5, 0x90
	v_ldexp_f32 v112, v40, v41
	v_mov_b32_e32 v41, s4
	v_add_u32_e32 v47, s4, v46
	v_readlane_b32 s4, v252, 19
	v_lshrrev_b32_e32 v40, 3, v158
	v_add_u32_e32 v159, 0, v0
	v_mad_u32_u24 v45, v98, s5, v41
	v_add_u32_e32 v160, s4, v103
	v_add_u32_e32 v0, s4, v0
	v_mov_b32_e32 v41, 0x2100
	s_movk_i32 s4, 0x210
	s_add_i32 s10, s10, s11
	v_mad_u32_u24 v162, v98, s4, v41
	v_mul_u32_u24_e32 v49, 0x90, v40
	v_mul_lo_u32 v163, v118, s4
	v_mul_lo_u32 v164, v119, s4
	v_mul_lo_u32 v165, v120, s4
	v_mul_lo_u32 v166, v121, s4
	v_add_u32_e32 v40, s10, v40
	s_movk_i32 s4, 0x3000
	v_mad_i64_i32 v[42:43], s[4:5], v40, s4, 0
	v_ashrrev_i32_e32 v41, 31, v40
	v_or_b32_e32 v42, v42, v46
	v_add_u32_e32 v169, s17, v119
	v_add_u32_e32 v170, s17, v118
	v_lshl_add_u64 v[118:119], s[28:29], 0, v[42:43]
	v_lshlrev_b64 v[42:43], 13, v[40:41]
	v_add_u32_e32 v40, 8, v40
	v_ashrrev_i32_e32 v41, 31, v40
	v_lshlrev_b64 v[40:41], 13, v[40:41]
	v_add_u32_e32 v44, 0, v102
	v_readlane_b32 s12, v253, 24
	v_mul_u32_u24_e32 v48, 0x110, v98
	v_or_b32_e32 v42, v42, v46
	v_or_b32_e32 v40, v40, v46
	s_ashr_i32 s1, s0, 31
	v_readlane_b32 s13, v253, 25
	v_add_u32_e32 v167, s17, v121
	v_add_u32_e32 v168, s17, v120
	v_lshl_add_u64 v[120:121], s[28:29], 0, v[42:43]
	v_lshl_add_u64 v[122:123], s[28:29], 0, v[40:41]
	v_add_u32_e32 v174, v44, v48
	v_add_u32_e32 v175, v45, v102
	v_add_u32_e32 v176, v47, v49
	s_waitcnt vmcnt(2)
	v_mov_b64_e32 v[44:45], v[84:85]
	v_mov_b64_e32 v[40:41], v[80:81]
	s_waitcnt vmcnt(1)
	v_mov_b64_e32 v[48:49], v[88:89]
	s_waitcnt vmcnt(0)
	v_mov_b64_e32 v[52:53], v[92:93]
	v_ashrrev_i32_e32 v3, 31, v2
	v_mov_b32_e32 v173, 0
	s_mov_b32 s3, 0
	v_mov_b32_e32 v113, v112
	v_mov_b32_e32 v114, v112
	v_mov_b32_e32 v115, v112
	v_lshl_add_u64 v[116:117], v[96:97], 1, s[12:13]
	v_mul_u32_u24_e32 v161, 0x210, v98
	v_add_u32_e32 v171, s0, v100
	v_add_u32_e32 v172, s0, v99
	s_lshl_b64 s[0:1], s[0:1], 1
	v_mov_b64_e32 v[46:47], v[86:87]
	v_mov_b64_e32 v[42:43], v[82:83]
	v_mov_b64_e32 v[50:51], v[90:91]
	v_mov_b64_e32 v[54:55], v[94:95]
	s_mov_b32 s22, 0
	s_cmp_eq_u64 s[38:39], 0
	s_cselect_b32 s99, 6, 0
	s_branch .LBB0_130

.LBB0_136:
	v_lshl_add_u64 v[140:141], v[118:119], 0, s[0:1]
	s_mov_b32 s4, 0xf501000
	v_add_co_u32_e32 v142, vcc, s4, v140
	s_nop 4
	v_pk_mul_f32 v[128:129], v[114:115], v[98:99]
	v_addc_co_u32_e32 v143, vcc, 0, v141, vcc
	s_waitcnt lgkmcnt(0)
	v_add_co_u32_e32 v80, vcc, 0xf519000, v140
	v_pk_mul_f32 v[130:131], v[112:113], v[96:97]
	s_nop 0
	v_addc_co_u32_e32 v81, vcc, 0, v141, vcc
	v_cvt_pk_bf16_f32 v88, v130, v131
	v_cvt_pk_bf16_f32 v89, v128, v129
	global_load_dwordx4 v[84:87], v[142:143], off nt
	s_nop 0
	global_load_dwordx4 v[80:83], v[80:81], off nt
	s_cmp_lt_u32 s22, s99
	s_cbranch_scc0 .Lmy_rdA
	v_add_u32_e32 v238, s3, v170
	v_add_u32_e32 v240, s3, v169
	v_add_u32_e32 v246, s3, v168
	v_add_u32_e32 v248, s3, v167
	v_add_u32_e32 v238, 0x80, v238
	v_add_u32_e32 v240, 0x80, v240
	v_add_u32_e32 v246, 0x80, v246
	v_add_u32_e32 v248, 0x80, v248
	v_ashrrev_i32_e32 v239, 31, v238
	v_ashrrev_i32_e32 v241, 31, v240
	v_ashrrev_i32_e32 v247, 31, v246
	v_ashrrev_i32_e32 v249, 31, v248
	v_lshlrev_b64 v[238:239], 9, v[238:239]
	v_lshlrev_b64 v[240:241], 9, v[240:241]
	v_lshlrev_b64 v[246:247], 9, v[246:247]
	v_lshlrev_b64 v[248:249], 9, v[248:249]
	v_lshl_add_u64 v[238:239], v[116:117], 0, v[238:239]
	v_lshl_add_u64 v[242:243], v[116:117], 0, v[240:241]
	v_lshl_add_u64 v[246:247], v[116:117], 0, v[246:247]
	v_lshl_add_u64 v[224:225], v[116:117], 0, v[248:249]
	global_load_dwordx4 v[238:241], v[238:239], off nt
	s_nop 0
	global_load_dwordx4 v[242:245], v[242:243], off nt
	s_nop 0
	global_load_dwordx4 v[246:249], v[246:247], off nt
	s_nop 0
	global_load_dwordx4 v[224:227], v[224:225], off nt
.Lmy_rdA:
	ds_write_b64 v175, v[88:89] offset:32
	v_add_u32_e32 v88, 0x2000, v174
	ds_read2_b64 v[96:99], v88 offset0:64 offset1:68
	ds_read2_b64 v[92:95], v88 offset0:72 offset1:76
	ds_read2_b64 v[100:103], v88 offset0:80 offset1:84
	ds_read2_b64 v[88:91], v88 offset0:88 offset1:92
	s_and_b64 vcc, exec, s[38:39]
	s_cbranch_vccnz .LBB0_166
	ds_read_b128 v[104:107], v136 offset:25856
	ds_read_b128 v[132:135], v136 offset:25920
	ds_read_b128 v[144:147], v136 offset:25984
	ds_read_b128 v[148:151], v136 offset:26048
	s_waitcnt lgkmcnt(7)
	v_mfma_f32_16x16x32_bf16 v[152:155], v[96:99], v[56:59], 0
	ds_read_b128 v[178:181], v136 offset:26112
	ds_read_b128 v[184:187], v136 offset:26176
	ds_read_b128 v[188:191], v136 offset:26240
	ds_read_b128 v[192:195], v136 offset:26304
	s_waitcnt lgkmcnt(10)
	v_mfma_f32_16x16x32_bf16 v[152:155], v[92:95], v[60:63], v[152:155]
	s_waitcnt lgkmcnt(9)
	v_mfma_f32_16x16x32_bf16 v[152:155], v[100:103], v[64:67], v[152:155]
	s_waitcnt lgkmcnt(8)
	v_mfma_f32_16x16x32_bf16 v[152:155], v[88:91], v[68:71], v[152:155]
	s_waitcnt lgkmcnt(7)
	v_mfma_f32_16x16x32_bf16 v[104:107], v[104:107], v[8:11], v[152:155]
	s_waitcnt lgkmcnt(6)
	v_mfma_f32_16x16x32_bf16 v[104:107], v[132:135], v[12:15], v[104:107]
	s_waitcnt lgkmcnt(5)
	v_mfma_f32_16x16x32_bf16 v[104:107], v[144:147], v[16:19], v[104:107]
	s_waitcnt lgkmcnt(4)
	v_mfma_f32_16x16x32_bf16 v[104:107], v[148:151], v[20:23], v[104:107]
	s_waitcnt lgkmcnt(3)
	v_mfma_f32_16x16x32_bf16 v[104:107], v[178:181], v[24:27], v[104:107]
	s_waitcnt lgkmcnt(2)
	v_mfma_f32_16x16x32_bf16 v[104:107], v[184:187], v[28:31], v[104:107]
	s_waitcnt lgkmcnt(1)
	v_mfma_f32_16x16x32_bf16 v[104:107], v[188:191], v[32:35], v[104:107]
	s_waitcnt lgkmcnt(0)
	v_mfma_f32_16x16x32_bf16 v[104:107], v[192:195], v[36:39], v[104:107]
	s_cbranch_execnz .LBB0_139

.LBB0_142:
	s_waitcnt vmcnt(5) lgkmcnt(2)
	s_cmp_lt_u32 s22, s99
	s_cbranch_scc1 .Lmy_wA1
	s_waitcnt vmcnt(1)
.Lmy_wA1:
	s_nop 4
	v_lshlrev_b32_e32 v92, 16, v84
	v_mul_f32_e32 v93, 0xbfb8aa3b, v92
	v_exp_f32_e32 v93, v93
	v_pk_mul_f32 v[136:137], v[114:115], v[106:107]
	v_pk_mul_f32 v[138:139], v[112:113], v[104:105]
	v_and_b32_e32 v84, 0xffff0000, v84
	s_waitcnt lgkmcnt(0)
	v_cvt_pk_bf16_f32 v88, v138, v139
	v_cvt_pk_bf16_f32 v89, v136, v137
	ds_write_b64 v175, v[88:89] offset:96
	ds_read_b128 v[88:91], v176
	v_add_f32_e32 v93, 1.0, v93
	v_rcp_f32_e32 v93, v93
	s_mov_b32 s4, 0x23700000
	v_lshl_add_u64 v[144:145], v[122:123], 0, s[0:1]
	v_mul_f32_e32 v92, v93, v92
	s_waitcnt lgkmcnt(0)
	v_lshlrev_b32_e32 v93, 16, v88
	v_mul_f32_e32 v92, v92, v93
	v_mul_f32_e32 v93, 0xbfb8aa3b, v84
	v_exp_f32_e32 v93, v93
	v_and_b32_e32 v88, 0xffff0000, v88
	v_add_f32_e32 v93, 1.0, v93
	v_rcp_f32_e32 v93, v93
	s_nop 0
	v_mul_f32_e32 v84, v93, v84
	v_mul_f32_e32 v84, v84, v88
	v_lshlrev_b32_e32 v88, 16, v85
	v_cvt_pk_bf16_f32 v84, v92, v84
	v_mul_f32_e32 v92, 0xbfb8aa3b, v88
	v_exp_f32_e32 v92, v92
	v_and_b32_e32 v85, 0xffff0000, v85
	v_add_f32_e32 v92, 1.0, v92
	v_rcp_f32_e32 v92, v92
	s_nop 0
	v_mul_f32_e32 v88, v92, v88
	v_lshlrev_b32_e32 v92, 16, v89
	v_mul_f32_e32 v88, v88, v92
	v_mul_f32_e32 v92, 0xbfb8aa3b, v85
	v_exp_f32_e32 v92, v92
	v_and_b32_e32 v89, 0xffff0000, v89
	v_add_f32_e32 v92, 1.0, v92
	v_rcp_f32_e32 v92, v92
	s_nop 0
	v_mul_f32_e32 v85, v92, v85
	v_mul_f32_e32 v85, v85, v89
	v_cvt_pk_bf16_f32 v85, v88, v85
	v_lshlrev_b32_e32 v88, 16, v86
	v_mul_f32_e32 v89, 0xbfb8aa3b, v88
	v_exp_f32_e32 v89, v89
	v_and_b32_e32 v86, 0xffff0000, v86
	v_add_f32_e32 v89, 1.0, v89
	v_rcp_f32_e32 v89, v89
	s_nop 0
	v_mul_f32_e32 v88, v89, v88
	v_lshlrev_b32_e32 v89, 16, v90
	v_mul_f32_e32 v88, v88, v89
	v_mul_f32_e32 v89, 0xbfb8aa3b, v86
	v_exp_f32_e32 v89, v89
	s_nop 0
	v_add_f32_e32 v89, 1.0, v89
	v_rcp_f32_e32 v89, v89
	s_nop 0
	v_mul_f32_e32 v86, v89, v86
	v_and_b32_e32 v89, 0xffff0000, v90
	v_mul_f32_e32 v86, v86, v89
	v_cvt_pk_bf16_f32 v86, v88, v86
	v_lshlrev_b32_e32 v88, 16, v87
	v_mul_f32_e32 v89, 0xbfb8aa3b, v88
	v_exp_f32_e32 v89, v89
	v_and_b32_e32 v87, 0xffff0000, v87
	v_add_f32_e32 v89, 1.0, v89
	v_rcp_f32_e32 v89, v89
	s_nop 0
	v_mul_f32_e32 v88, v89, v88
	v_lshlrev_b32_e32 v89, 16, v91
	v_mul_f32_e32 v88, v88, v89
	v_mul_f32_e32 v89, 0xbfb8aa3b, v87
	v_exp_f32_e32 v89, v89
	s_nop 0
	v_add_f32_e32 v89, 1.0, v89
	v_rcp_f32_e32 v89, v89
	s_nop 0
	v_mul_f32_e32 v87, v89, v87
	v_and_b32_e32 v89, 0xffff0000, v91
	v_mul_f32_e32 v87, v87, v89
	v_cvt_pk_bf16_f32 v87, v88, v87
	v_lshl_add_u64 v[88:89], v[120:121], 0, s[0:1]
	v_add_co_u32_e32 v146, vcc, s4, v88
	s_waitcnt vmcnt(4)
	s_cmp_lt_u32 s22, s99
	s_cbranch_scc1 .Lmy_wA2
	s_waitcnt vmcnt(0)
; #define LBAR() do { asm volatile("s_waitcnt lgkmcnt(0)" ::: "memory"); __builtin_amdgcn_s_barrier(); asm volatile("" ::: "memory"); } while (0)
; #define RO_WRITE(rv, rs, buf) do { _Pragma("unroll") for (int i = 0; i < 2; ++i) { const int q = tid + 512 * i; *(LAS v4u*)(lds + (buf) + (q >> 4) * VROW + (q & 15) * 16) = rv[i]; } \
;             if (cross) { _Pragma("unroll") for (int i = 0; i < 4; ++i) { const int q = tid + 512 * i; *(LAS v4u*)(lds + (buf) + VTB + (q >> 5) * SROW + (q & 31) * 16) = rs[i]; } } } while (0)
; __device__ __forceinline__ void ret_out_phase(LAS unsigned char* lds, const bf16* PROJ, const bf16* KVT, const bf16* ST, bf16* Y, float* RN, int G, int bid) {
;     ...
; #pragma unroll 1
;         for (int ec = 0; ec < 8; ec += 2) {
;             RO_BODY(ec, BUF0);
;             RO_WRITE(rvA, rsA, BUF1); LBAR();
;             if (ec + 2 < 8) RO_LOAD(rvA, rsA, ec + 2);
;             RO_BODY(ec + 1, BUF1);
;             if (ec + 2 < 8) { RO_WRITE(rvA, rsA, BUF0); LBAR(); RO_LOAD(rvA, rsA, ec + 3); }
.Lmy_wA2:
	v_lshlrev_b32_e32 v88, 16, v80
	v_addc_co_u32_e32 v147, vcc, 0, v89, vcc
	v_mul_f32_e32 v89, 0xbfb8aa3b, v88
	v_exp_f32_e32 v89, v89
	global_store_dwordx4 v[146:147], v[84:87], off nt
	ds_read_b128 v[84:87], v176 offset:1152
	v_and_b32_e32 v80, 0xffff0000, v80
	v_add_f32_e32 v89, 1.0, v89
	v_rcp_f32_e32 v89, v89
	s_nop 0
	v_mul_f32_e32 v88, v89, v88
	s_waitcnt lgkmcnt(0)
	v_lshlrev_b32_e32 v89, 16, v84
	v_mul_f32_e32 v88, v88, v89
	v_mul_f32_e32 v89, 0xbfb8aa3b, v80
	v_exp_f32_e32 v89, v89
	v_and_b32_e32 v84, 0xffff0000, v84
	v_add_f32_e32 v89, 1.0, v89
	v_rcp_f32_e32 v89, v89
	s_nop 0
	v_mul_f32_e32 v80, v89, v80
	v_mul_f32_e32 v80, v80, v84
	v_lshlrev_b32_e32 v84, 16, v81
	v_cvt_pk_bf16_f32 v80, v88, v80
	v_mul_f32_e32 v88, 0xbfb8aa3b, v84
	v_exp_f32_e32 v88, v88
	v_and_b32_e32 v81, 0xffff0000, v81
	v_add_f32_e32 v88, 1.0, v88
	v_rcp_f32_e32 v88, v88
	s_nop 0
	v_mul_f32_e32 v84, v88, v84
	v_lshlrev_b32_e32 v88, 16, v85
	v_mul_f32_e32 v84, v84, v88
	v_mul_f32_e32 v88, 0xbfb8aa3b, v81
	v_exp_f32_e32 v88, v88
	v_and_b32_e32 v85, 0xffff0000, v85
	v_add_f32_e32 v88, 1.0, v88
	v_rcp_f32_e32 v88, v88
	s_nop 0
	v_mul_f32_e32 v81, v88, v81
	v_mul_f32_e32 v81, v81, v85
	v_cvt_pk_bf16_f32 v81, v84, v81
	v_lshlrev_b32_e32 v84, 16, v82
	v_mul_f32_e32 v85, 0xbfb8aa3b, v84
	v_exp_f32_e32 v85, v85
	v_and_b32_e32 v82, 0xffff0000, v82
	v_add_f32_e32 v85, 1.0, v85
	v_rcp_f32_e32 v85, v85
	s_nop 0
	v_mul_f32_e32 v84, v85, v84
	v_lshlrev_b32_e32 v85, 16, v86
	v_mul_f32_e32 v84, v84, v85
	v_mul_f32_e32 v85, 0xbfb8aa3b, v82
	v_exp_f32_e32 v85, v85
	s_nop 0
	v_add_f32_e32 v85, 1.0, v85
	v_rcp_f32_e32 v85, v85
	s_nop 0
	v_mul_f32_e32 v82, v85, v82
	v_and_b32_e32 v85, 0xffff0000, v86
	v_mul_f32_e32 v82, v82, v85
	v_cvt_pk_bf16_f32 v82, v84, v82
	v_lshlrev_b32_e32 v84, 16, v83
	v_mul_f32_e32 v85, 0xbfb8aa3b, v84
	v_exp_f32_e32 v85, v85
	v_and_b32_e32 v83, 0xffff0000, v83
	v_add_f32_e32 v85, 1.0, v85
	v_rcp_f32_e32 v85, v85
	s_nop 0
	v_mul_f32_e32 v84, v85, v84
	v_lshlrev_b32_e32 v85, 16, v87
	v_mul_f32_e32 v84, v84, v85
	v_mul_f32_e32 v85, 0xbfb8aa3b, v83
	v_exp_f32_e32 v85, v85
	s_nop 0
	v_add_f32_e32 v85, 1.0, v85
	v_rcp_f32_e32 v85, v85
	s_nop 0
	v_mul_f32_e32 v83, v85, v83
	v_and_b32_e32 v85, 0xffff0000, v87
	v_mul_f32_e32 v83, v83, v85
	v_cvt_pk_bf16_f32 v83, v84, v83
	v_add_co_u32_e32 v84, vcc, 0x23700000, v144
	s_nop 1
	v_addc_co_u32_e32 v85, vcc, 0, v145, vcc
	s_and_b64 vcc, exec, s[38:39]
	global_store_dwordx4 v[84:85], v[80:83], off nt
	ds_write_b128 v156, v[76:79] offset:51200
	ds_write_b128 v157, v[72:75] offset:51200
	s_cbranch_vccnz .LBB0_144
	v_add_u32_e32 v80, v160, v163
	ds_write_b128 v80, v[40:43]
	v_add_u32_e32 v80, v160, v164
	ds_write_b128 v80, v[44:47]
	v_add_u32_e32 v80, v160, v165
	ds_write_b128 v80, v[48:51]
	v_add_u32_e32 v80, v160, v166
	ds_write_b128 v80, v[52:55]
.LBB0_144:
	s_cmp_lt_u32 s22, 6
	s_waitcnt lgkmcnt(0)
	s_barrier
	s_cselect_b64 s[10:11], -1, 0
	s_cmp_gt_u32 s22, 5
	s_cselect_b64 s[4:5], -1, 0
	s_and_b64 vcc, exec, s[4:5]
	v_add_u32_e32 v178, s3, v172
	v_add_u32_e32 v177, s3, v171
	s_cbranch_vccnz .LBB0_147
	v_add_u32_e32 v72, 0x880, v178
	s_movk_i32 s23, 0x4080
	v_add_u32_e32 v74, 0x880, v177
	v_mad_i64_i32 v[72:73], s[12:13], v72, s23, v[108:109]
	v_mad_i64_i32 v[74:75], s[12:13], v74, s23, v[108:109]
	global_load_dwordx4 v[76:79], v[72:73], off nt
	s_nop 0
	global_load_dwordx4 v[72:75], v[74:75], off nt
.LBB0_147:
	v_add_u32_e32 v80, 0xc800, v174
	ds_read2_b64 v[88:91], v80 offset1:4
	ds_read2_b64 v[84:87], v80 offset0:8 offset1:12
	ds_read2_b64 v[92:95], v80 offset0:16 offset1:20
	ds_read2_b64 v[80:83], v80 offset0:24 offset1:28
	s_and_b64 vcc, exec, s[38:39]
	s_cbranch_vccnz .LBB0_168
	v_add_u32_e32 v179, v0, v161
	ds_read_b128 v[96:99], v179
	ds_read_b128 v[100:103], v179 offset:64
	ds_read_b128 v[104:107], v179 offset:128
	ds_read_b128 v[148:151], v179 offset:192
	s_waitcnt lgkmcnt(7)
	v_mfma_f32_16x16x32_bf16 v[152:155], v[88:91], v[56:59], 0
	ds_read_b128 v[184:187], v179 offset:256
	ds_read_b128 v[188:191], v179 offset:320
	ds_read_b128 v[192:195], v179 offset:384
	ds_read_b128 v[196:199], v179 offset:448
	s_waitcnt lgkmcnt(10)
	v_mfma_f32_16x16x32_bf16 v[152:155], v[84:87], v[60:63], v[152:155]
	s_waitcnt lgkmcnt(9)
	v_mfma_f32_16x16x32_bf16 v[152:155], v[92:95], v[64:67], v[152:155]
	s_waitcnt lgkmcnt(8)
	v_mfma_f32_16x16x32_bf16 v[152:155], v[80:83], v[68:71], v[152:155]
	s_waitcnt lgkmcnt(7)
	v_mfma_f32_16x16x32_bf16 v[96:99], v[96:99], v[8:11], v[152:155]
	s_waitcnt lgkmcnt(6)
	v_mfma_f32_16x16x32_bf16 v[96:99], v[100:103], v[12:15], v[96:99]
	s_waitcnt lgkmcnt(5)
	v_mfma_f32_16x16x32_bf16 v[96:99], v[104:107], v[16:19], v[96:99]
	s_waitcnt lgkmcnt(4)
	v_mfma_f32_16x16x32_bf16 v[96:99], v[148:151], v[20:23], v[96:99]
	s_waitcnt lgkmcnt(3)
	v_mfma_f32_16x16x32_bf16 v[96:99], v[184:187], v[24:27], v[96:99]
	s_waitcnt lgkmcnt(2)
	v_mfma_f32_16x16x32_bf16 v[96:99], v[188:191], v[28:31], v[96:99]
	s_waitcnt lgkmcnt(1)
	v_mfma_f32_16x16x32_bf16 v[96:99], v[192:195], v[32:35], v[96:99]
	s_waitcnt lgkmcnt(0)
	v_mfma_f32_16x16x32_bf16 v[96:99], v[196:199], v[36:39], v[96:99]
	s_cbranch_execnz .LBB0_150

.LBB0_153:
	s_waitcnt lgkmcnt(0)
	v_add_co_u32_e32 v80, vcc, 0xf519000, v140
	s_nop 5
	v_pk_mul_f32 v[152:153], v[114:115], v[98:99]
	v_addc_co_u32_e32 v81, vcc, 0, v141, vcc
	v_pk_mul_f32 v[154:155], v[112:113], v[96:97]
	s_and_b64 vcc, exec, s[38:39]
	v_cvt_pk_bf16_f32 v88, v154, v155
	v_cvt_pk_bf16_f32 v89, v152, v153
	global_load_dwordx4 v[84:87], v[142:143], off offset:128 nt
	s_nop 0
	global_load_dwordx4 v[80:83], v[80:81], off offset:128 nt
	s_cmp_lt_u32 s22, s99
	s_cbranch_scc0 .Lmy_rdB
	v_add_u32_e32 v40, s3, v170
	v_add_u32_e32 v42, s3, v169
	v_add_u32_e32 v48, s3, v168
	v_add_u32_e32 v50, s3, v167
	v_add_u32_e32 v40, 0xc0, v40
	v_add_u32_e32 v42, 0xc0, v42
	v_add_u32_e32 v48, 0xc0, v48
	v_add_u32_e32 v50, 0xc0, v50
	v_ashrrev_i32_e32 v41, 31, v40
	v_ashrrev_i32_e32 v43, 31, v42
	v_ashrrev_i32_e32 v49, 31, v48
	v_ashrrev_i32_e32 v51, 31, v50
	v_lshlrev_b64 v[40:41], 9, v[40:41]
	v_lshlrev_b64 v[42:43], 9, v[42:43]
	v_lshlrev_b64 v[48:49], 9, v[48:49]
	v_lshlrev_b64 v[50:51], 9, v[50:51]
	v_lshl_add_u64 v[40:41], v[116:117], 0, v[40:41]
	v_lshl_add_u64 v[44:45], v[116:117], 0, v[42:43]
	v_lshl_add_u64 v[48:49], v[116:117], 0, v[48:49]
	v_lshl_add_u64 v[52:53], v[116:117], 0, v[50:51]
	global_load_dwordx4 v[40:43], v[40:41], off nt
	s_nop 0
	global_load_dwordx4 v[44:47], v[44:45], off nt
	s_nop 0
	global_load_dwordx4 v[48:51], v[48:49], off nt
	s_nop 0
	global_load_dwordx4 v[52:55], v[52:53], off nt
.Lmy_rdB:
	ds_write_b64 v175, v[88:89] offset:32
	v_add_u32_e32 v88, 0xe800, v174
	ds_read2_b64 v[96:99], v88 offset0:64 offset1:68
	ds_read2_b64 v[92:95], v88 offset0:72 offset1:76
	ds_read2_b64 v[100:103], v88 offset0:80 offset1:84
	ds_read2_b64 v[88:91], v88 offset0:88 offset1:92
	s_cbranch_vccnz .LBB0_170
	ds_read_b128 v[104:107], v179 offset:8448
	ds_read_b128 v[140:143], v179 offset:8512
	ds_read_b128 v[184:187], v179 offset:8576
	ds_read_b128 v[188:191], v179 offset:8640
	s_waitcnt lgkmcnt(7)
	v_mfma_f32_16x16x32_bf16 v[192:195], v[96:99], v[56:59], 0
	ds_read_b128 v[196:199], v179 offset:8704
	ds_read_b128 v[200:203], v179 offset:8768
	ds_read_b128 v[204:207], v179 offset:8832
	ds_read_b128 v[230:233], v179 offset:8896
	s_waitcnt lgkmcnt(10)
	v_mfma_f32_16x16x32_bf16 v[192:195], v[92:95], v[60:63], v[192:195]
	s_waitcnt lgkmcnt(9)
	v_mfma_f32_16x16x32_bf16 v[192:195], v[100:103], v[64:67], v[192:195]
	s_waitcnt lgkmcnt(8)
	v_mfma_f32_16x16x32_bf16 v[192:195], v[88:91], v[68:71], v[192:195]
	s_waitcnt lgkmcnt(7)
	v_mfma_f32_16x16x32_bf16 v[104:107], v[104:107], v[8:11], v[192:195]
	s_waitcnt lgkmcnt(6)
	v_mfma_f32_16x16x32_bf16 v[104:107], v[140:143], v[12:15], v[104:107]
	s_waitcnt lgkmcnt(5)
	v_mfma_f32_16x16x32_bf16 v[104:107], v[184:187], v[16:19], v[104:107]
	s_waitcnt lgkmcnt(4)
	v_mfma_f32_16x16x32_bf16 v[104:107], v[188:191], v[20:23], v[104:107]
	s_waitcnt lgkmcnt(3)
	v_mfma_f32_16x16x32_bf16 v[104:107], v[196:199], v[24:27], v[104:107]
	s_waitcnt lgkmcnt(2)
	v_mfma_f32_16x16x32_bf16 v[104:107], v[200:203], v[28:31], v[104:107]
	s_waitcnt lgkmcnt(1)
	v_mfma_f32_16x16x32_bf16 v[104:107], v[204:207], v[32:35], v[104:107]
	s_waitcnt lgkmcnt(0)
	v_mfma_f32_16x16x32_bf16 v[104:107], v[230:233], v[36:39], v[104:107]
	s_cbranch_execnz .LBB0_156

; #define LBAR() do { asm volatile("s_waitcnt lgkmcnt(0)" ::: "memory"); __builtin_amdgcn_s_barrier(); asm volatile("" ::: "memory"); } while (0)
; #define RO_WRITE(rv, rs, buf) do { _Pragma("unroll") for (int i = 0; i < 2; ++i) { const int q = tid + 512 * i; *(LAS v4u*)(lds + (buf) + (q >> 4) * VROW + (q & 15) * 16) = rv[i]; } \
;             if (cross) { _Pragma("unroll") for (int i = 0; i < 4; ++i) { const int q = tid + 512 * i; *(LAS v4u*)(lds + (buf) + VTB + (q >> 5) * SROW + (q & 31) * 16) = rs[i]; } } } while (0)
; __device__ __forceinline__ void ret_out_phase(LAS unsigned char* lds, const bf16* PROJ, const bf16* KVT, const bf16* ST, bf16* Y, float* RN, int G, int bid) {
;     ...
; #pragma unroll 1
;         for (int ec = 0; ec < 8; ec += 2) {
;             RO_BODY(ec, BUF0);
;             RO_WRITE(rvA, rsA, BUF1); LBAR();
;             if (ec + 2 < 8) RO_LOAD(rvA, rsA, ec + 2);
;             RO_BODY(ec + 1, BUF1);
;             if (ec + 2 < 8) { RO_WRITE(rvA, rsA, BUF0); LBAR(); RO_LOAD(rvA, rsA, ec + 3); }
.LBB0_159:
	s_waitcnt vmcnt(5) lgkmcnt(3)
	s_cmp_lt_u32 s22, s99
	s_cbranch_scc1 .Lmy_wB1
	s_waitcnt vmcnt(1)
.Lmy_wB1:
	s_nop 0
	v_lshlrev_b32_e32 v96, 16, v84
	v_mul_f32_e32 v97, 0xbfb8aa3b, v96
	v_exp_f32_e32 v97, v97
	s_waitcnt lgkmcnt(2)
	s_nop 1
	v_pk_mul_f32 v[92:93], v[114:115], v[106:107]
	v_pk_mul_f32 v[94:95], v[112:113], v[104:105]
	v_and_b32_e32 v84, 0xffff0000, v84
	s_waitcnt lgkmcnt(0)
	v_cvt_pk_bf16_f32 v88, v94, v95
	v_cvt_pk_bf16_f32 v89, v92, v93
	ds_write_b64 v175, v[88:89] offset:96
	ds_read_b128 v[88:91], v176
	v_add_f32_e32 v97, 1.0, v97
	v_rcp_f32_e32 v97, v97
	s_nop 0
	v_mul_f32_e32 v96, v97, v96
	s_waitcnt lgkmcnt(0)
	v_lshlrev_b32_e32 v97, 16, v88
	v_mul_f32_e32 v96, v96, v97
	v_mul_f32_e32 v97, 0xbfb8aa3b, v84
	v_exp_f32_e32 v97, v97
	v_and_b32_e32 v88, 0xffff0000, v88
	v_add_f32_e32 v97, 1.0, v97
	v_rcp_f32_e32 v97, v97
	s_nop 0
	v_mul_f32_e32 v84, v97, v84
	v_mul_f32_e32 v84, v84, v88
	v_lshlrev_b32_e32 v88, 16, v85
	v_cvt_pk_bf16_f32 v84, v96, v84
	v_mul_f32_e32 v96, 0xbfb8aa3b, v88
	v_exp_f32_e32 v96, v96
	v_and_b32_e32 v85, 0xffff0000, v85
	v_add_f32_e32 v96, 1.0, v96
	v_rcp_f32_e32 v96, v96
	s_nop 0
	v_mul_f32_e32 v88, v96, v88
	v_lshlrev_b32_e32 v96, 16, v89
	v_mul_f32_e32 v88, v88, v96
	v_mul_f32_e32 v96, 0xbfb8aa3b, v85
	v_exp_f32_e32 v96, v96
	v_and_b32_e32 v89, 0xffff0000, v89
	v_add_f32_e32 v96, 1.0, v96
	v_rcp_f32_e32 v96, v96
	s_nop 0
	v_mul_f32_e32 v85, v96, v85
	v_mul_f32_e32 v85, v85, v89
	v_cvt_pk_bf16_f32 v85, v88, v85
	v_lshlrev_b32_e32 v88, 16, v86
	v_mul_f32_e32 v89, 0xbfb8aa3b, v88
	v_exp_f32_e32 v89, v89
	v_and_b32_e32 v86, 0xffff0000, v86
	v_add_f32_e32 v89, 1.0, v89
	v_rcp_f32_e32 v89, v89
	s_nop 0
	v_mul_f32_e32 v88, v89, v88
	v_lshlrev_b32_e32 v89, 16, v90
	v_mul_f32_e32 v88, v88, v89
	v_mul_f32_e32 v89, 0xbfb8aa3b, v86
	v_exp_f32_e32 v89, v89
	s_nop 0
	v_add_f32_e32 v89, 1.0, v89
	v_rcp_f32_e32 v89, v89
	s_nop 0
	v_mul_f32_e32 v86, v89, v86
	v_and_b32_e32 v89, 0xffff0000, v90
	v_mul_f32_e32 v86, v86, v89
	v_cvt_pk_bf16_f32 v86, v88, v86
	v_lshlrev_b32_e32 v88, 16, v87
	v_mul_f32_e32 v89, 0xbfb8aa3b, v88
	v_exp_f32_e32 v89, v89
	v_and_b32_e32 v87, 0xffff0000, v87
	v_add_f32_e32 v89, 1.0, v89
	v_rcp_f32_e32 v89, v89
	s_nop 0
	v_mul_f32_e32 v88, v89, v88
	v_lshlrev_b32_e32 v89, 16, v91
	v_mul_f32_e32 v88, v88, v89
	v_mul_f32_e32 v89, 0xbfb8aa3b, v87
	v_exp_f32_e32 v89, v89
	s_nop 0
	v_add_f32_e32 v89, 1.0, v89
	v_rcp_f32_e32 v89, v89
	s_nop 0
	v_mul_f32_e32 v87, v89, v87
	v_and_b32_e32 v89, 0xffff0000, v91
	v_mul_f32_e32 v87, v87, v89
	v_cvt_pk_bf16_f32 v87, v88, v87
	s_waitcnt vmcnt(4)
	s_cmp_lt_u32 s22, s99
	s_cbranch_scc1 .Lmy_wB2
	s_waitcnt vmcnt(0)
.Lmy_wB2:
	v_lshlrev_b32_e32 v88, 16, v80
	v_mul_f32_e32 v89, 0xbfb8aa3b, v88
	v_exp_f32_e32 v89, v89
	global_store_dwordx4 v[146:147], v[84:87], off offset:128 nt
	ds_read_b128 v[84:87], v176 offset:1152
	v_and_b32_e32 v80, 0xffff0000, v80
	v_add_f32_e32 v89, 1.0, v89
	v_rcp_f32_e32 v89, v89
	s_nop 0
	v_mul_f32_e32 v88, v89, v88
	s_waitcnt lgkmcnt(0)
	v_lshlrev_b32_e32 v89, 16, v84
	v_mul_f32_e32 v88, v88, v89
	v_mul_f32_e32 v89, 0xbfb8aa3b, v80
	v_exp_f32_e32 v89, v89
	v_and_b32_e32 v84, 0xffff0000, v84
	v_add_f32_e32 v89, 1.0, v89
	v_rcp_f32_e32 v89, v89
	s_nop 0
	v_mul_f32_e32 v80, v89, v80
	v_mul_f32_e32 v80, v80, v84
	v_lshlrev_b32_e32 v84, 16, v81
	v_cvt_pk_bf16_f32 v80, v88, v80
	v_mul_f32_e32 v88, 0xbfb8aa3b, v84
	v_exp_f32_e32 v88, v88
	v_and_b32_e32 v81, 0xffff0000, v81
	v_add_f32_e32 v88, 1.0, v88
	v_rcp_f32_e32 v88, v88
	s_nop 0
	v_mul_f32_e32 v84, v88, v84
	v_lshlrev_b32_e32 v88, 16, v85
	v_mul_f32_e32 v84, v84, v88
	v_mul_f32_e32 v88, 0xbfb8aa3b, v81
	v_exp_f32_e32 v88, v88
	v_and_b32_e32 v85, 0xffff0000, v85
	v_add_f32_e32 v88, 1.0, v88
	v_rcp_f32_e32 v88, v88
	s_nop 0
	v_mul_f32_e32 v81, v88, v81
	v_mul_f32_e32 v81, v81, v85
	v_cvt_pk_bf16_f32 v81, v84, v81
	v_lshlrev_b32_e32 v84, 16, v82
	v_mul_f32_e32 v85, 0xbfb8aa3b, v84
	v_exp_f32_e32 v85, v85
	v_and_b32_e32 v82, 0xffff0000, v82
	v_add_f32_e32 v85, 1.0, v85
	v_rcp_f32_e32 v85, v85
	s_nop 0
	v_mul_f32_e32 v84, v85, v84
	v_lshlrev_b32_e32 v85, 16, v86
	v_mul_f32_e32 v84, v84, v85
	v_mul_f32_e32 v85, 0xbfb8aa3b, v82
	v_exp_f32_e32 v85, v85
	s_nop 0
	v_add_f32_e32 v85, 1.0, v85
	v_rcp_f32_e32 v85, v85
	s_nop 0
	v_mul_f32_e32 v82, v85, v82
	v_and_b32_e32 v85, 0xffff0000, v86
	v_mul_f32_e32 v82, v82, v85
	v_cvt_pk_bf16_f32 v82, v84, v82
	v_lshlrev_b32_e32 v84, 16, v83
	v_mul_f32_e32 v85, 0xbfb8aa3b, v84
	v_exp_f32_e32 v85, v85
	v_and_b32_e32 v83, 0xffff0000, v83
	v_add_f32_e32 v85, 1.0, v85
	v_rcp_f32_e32 v85, v85
	s_nop 0
	v_mul_f32_e32 v84, v85, v84
	v_lshlrev_b32_e32 v85, 16, v87
	v_mul_f32_e32 v84, v84, v85
	v_mul_f32_e32 v85, 0xbfb8aa3b, v83
	v_exp_f32_e32 v85, v85
	s_nop 0
	v_add_f32_e32 v85, 1.0, v85
	v_rcp_f32_e32 v85, v85
	s_nop 0
	v_mul_f32_e32 v83, v85, v83
	v_and_b32_e32 v85, 0xffff0000, v87
	v_mul_f32_e32 v83, v83, v85
	v_cvt_pk_bf16_f32 v83, v84, v83
	v_add_co_u32_e32 v84, vcc, 0x23700000, v144
	s_nop 1
	v_addc_co_u32_e32 v85, vcc, 0, v145, vcc
	s_andn2_b64 vcc, exec, s[10:11]
	global_store_dwordx4 v[84:85], v[80:83], off offset:128 nt
	s_cbranch_vccnz .LBB0_129
	s_and_b64 vcc, exec, s[38:39]
	ds_write_b128 v156, v[76:79]
	ds_write_b128 v157, v[72:75]
	s_cbranch_vccnz .LBB0_162
	v_add_u32_e32 v72, v110, v163
	ds_write_b128 v72, v[238:241] offset:17408
	v_add_u32_e32 v72, v110, v164
	ds_write_b128 v72, v[242:245] offset:17408
	v_add_u32_e32 v72, v110, v165
	ds_write_b128 v72, v[246:249] offset:17408
	v_add_u32_e32 v72, v110, v166
	ds_write_b128 v72, v[224:227] offset:17408
.LBB0_162:
	v_add_u32_e32 v72, 0x8c0, v178
	s_movk_i32 s12, 0x4080
	v_add_u32_e32 v74, 0x8c0, v177
	s_waitcnt lgkmcnt(0)
	s_barrier
	v_mad_i64_i32 v[72:73], s[10:11], v72, s12, v[108:109]
	v_mad_i64_i32 v[74:75], s[10:11], v74, s12, v[108:109]
	global_load_dwordx4 v[76:79], v[72:73], off nt
	s_nop 0
	global_load_dwordx4 v[72:75], v[74:75], off nt
	s_branch .LBB0_129
